# mqk prologue: weight staging loads issued before the XM pull, only they are waited for; the pull stays in flight into the loop
# baseline (speedup 1.0000x reference)
; #define MQ_LOAD(dst, mm) do { const int tk_ = row0 + 16 * (mm) + (lane & 15), s_ = tk_ & (SEQL - 1); \
;                 _Pragma("unroll") for (int j = 0; j < 4; ++j) dst[j] = (s_ - 3 + j >= 0) ? *(const u32x4*)(XM + (size_t)(tk_ - 3 + j) * 2048 + c0) : (u32x4){0u, 0u, 0u, 0u}; } while (0)
; __device__ void mqk_phase(const Params& p, unsigned char* smem) {
;     ...
;     for (int tile = blockIdx.x; tile < 256; tile += gridDim.x) {
;         const int row0 = tile * 64;
;         f32x4 acc[4];
; #pragma unroll
;         for (int m = 0; m < 4; ++m) acc[m] = (f32x4){0.f, 0.f, 0.f, 0.f};
;         for (int ks = 0; ks < 8; ++ks) {
;             const int c0 = 256 * wave + 32 * ks + 8 * (lane >> 4);
;             float cw[4][8], cbv[8];
; #pragma unroll
;             for (int j = 0; j < 4; ++j) { const f32x4 a = *(const f32x4*)(p.in[10] + j * 2048 + c0), b = *(const f32x4*)(p.in[10] + j * 2048 + c0 + 4);
; #pragma unroll
;                 for (int i = 0; i < 4; ++i) { cw[j][i] = a[i]; cw[j][4 + i] = b[i]; } }
;             { const f32x4 a = *(const f32x4*)(p.in[11] + c0), b = *(const f32x4*)(p.in[11] + c0 + 4);
; #pragma unroll
;               for (int i = 0; i < 4; ++i) { cbv[i] = a[i]; cbv[4 + i] = b[i]; } }
;             const bf16x8 bq = *(const bf16x8*)(WG + (size_t)(lane & 15) * 6144 + c0), bk = *(const bf16x8*)(WG + (size_t)(lane & 15) * 6144 + 2048 + c0), bv = *(const bf16x8*)(WG + (size_t)(lane & 15) * 6144 + 4096 + c0);
;             const float* wqp = p.in[12] + (size_t)(c0 >> 2) * 16; const float* wkp = p.in[13] + (size_t)(c0 >> 2) * 16; const float* wvp = p.in[14] + (size_t)(c0 >> 2) * 16;
;             u32x4 xraw[4];
;     ...
;             MQ_LOAD(xraw, 0);
.LBB0_299:
	v_and_b32_e32 v118, 0x3ff, v0
	v_lshlrev_b32_e32 v118, 4, v118
	v_add_u32_e32 v119, 0x2000, v118
	v_add_u32_e32 v120, 0x4000, v118
	v_add_u32_e32 v121, 0x6000, v118
	global_load_dwordx4 v[70:73], v118, s[80:81]
	global_load_dwordx4 v[74:77], v119, s[80:81]
	global_load_dwordx4 v[78:81], v120, s[80:81]
	global_load_dwordx4 v[82:85], v121, s[80:81]
	global_load_dwordx4 v[86:89], v118, s[76:77]
	global_load_dwordx4 v[90:93], v119, s[76:77]
	global_load_dwordx4 v[94:97], v120, s[76:77]
	global_load_dwordx4 v[98:101], v121, s[76:77]
	global_load_dwordx4 v[102:105], v118, s[78:79]
	global_load_dwordx4 v[106:109], v119, s[78:79]
	global_load_dwordx4 v[110:113], v120, s[78:79]
	global_load_dwordx4 v[114:117], v121, s[78:79]
	s_lshl_b32 s2, s50, 18
	s_sub_i32 s2, s2, 0x3000
	s_max_i32 s2, s2, 0
	v_and_b32_e32 v130, 0x3ff, v0
	v_lshlrev_b32_e32 v130, 4, v130
	v_add_u32_e32 v130, s2, v130
	global_load_dwordx4 v[252:255], v130, s[0:1]
	v_add_u32_e32 v130, 0x2000, v130
	global_load_dwordx4 v[252:255], v130, s[0:1]
	v_add_u32_e32 v130, 0x2000, v130
	global_load_dwordx4 v[252:255], v130, s[0:1]
	v_add_u32_e32 v130, 0x2000, v130
	global_load_dwordx4 v[252:255], v130, s[0:1]
	v_add_u32_e32 v130, 0x2000, v130
	global_load_dwordx4 v[252:255], v130, s[0:1]
	v_add_u32_e32 v130, 0x2000, v130
	global_load_dwordx4 v[252:255], v130, s[0:1]
	v_add_u32_e32 v130, 0x2000, v130
	global_load_dwordx4 v[252:255], v130, s[0:1]
	v_add_u32_e32 v130, 0x2000, v130
	global_load_dwordx4 v[252:255], v130, s[0:1]
	v_add_u32_e32 v130, 0x2000, v130
	global_load_dwordx4 v[252:255], v130, s[0:1]
	v_add_u32_e32 v130, 0x2000, v130
	global_load_dwordx4 v[252:255], v130, s[0:1]
	v_add_u32_e32 v130, 0x2000, v130
	global_load_dwordx4 v[252:255], v130, s[0:1]
	v_add_u32_e32 v130, 0x2000, v130
	global_load_dwordx4 v[252:255], v130, s[0:1]
	v_add_u32_e32 v130, 0x2000, v130
	global_load_dwordx4 v[252:255], v130, s[0:1]
	v_add_u32_e32 v130, 0x2000, v130
	global_load_dwordx4 v[252:255], v130, s[0:1]
	v_add_u32_e32 v130, 0x2000, v130
	global_load_dwordx4 v[252:255], v130, s[0:1]
	v_add_u32_e32 v130, 0x2000, v130
	global_load_dwordx4 v[252:255], v130, s[0:1]
	v_add_u32_e32 v130, 0x2000, v130
	global_load_dwordx4 v[252:255], v130, s[0:1]
	v_add_u32_e32 v130, 0x2000, v130
	global_load_dwordx4 v[252:255], v130, s[0:1]
	v_add_u32_e32 v130, 0x2000, v130
	global_load_dwordx4 v[252:255], v130, s[0:1]
	v_add_u32_e32 v130, 0x2000, v130
	global_load_dwordx4 v[252:255], v130, s[0:1]
	v_add_u32_e32 v130, 0x2000, v130
	global_load_dwordx4 v[252:255], v130, s[0:1]
	v_add_u32_e32 v130, 0x2000, v130
	global_load_dwordx4 v[252:255], v130, s[0:1]
	v_add_u32_e32 v130, 0x2000, v130
	global_load_dwordx4 v[252:255], v130, s[0:1]
	v_add_u32_e32 v130, 0x2000, v130
	global_load_dwordx4 v[252:255], v130, s[0:1]
	v_add_u32_e32 v130, 0x2000, v130
	global_load_dwordx4 v[252:255], v130, s[0:1]
	v_add_u32_e32 v130, 0x2000, v130
	global_load_dwordx4 v[252:255], v130, s[0:1]
	v_add_u32_e32 v130, 0x2000, v130
	global_load_dwordx4 v[252:255], v130, s[0:1]
	v_add_u32_e32 v130, 0x2000, v130
	global_load_dwordx4 v[252:255], v130, s[0:1]
	v_add_u32_e32 v130, 0x2000, v130
	global_load_dwordx4 v[252:255], v130, s[0:1]
	v_add_u32_e32 v130, 0x2000, v130
	global_load_dwordx4 v[252:255], v130, s[0:1]
	v_add_u32_e32 v130, 0x2000, v130
	global_load_dwordx4 v[252:255], v130, s[0:1]
	v_add_u32_e32 v130, 0x2000, v130
	global_load_dwordx4 v[252:255], v130, s[0:1]
	v_add_u32_e32 v130, 0x2000, v130
	global_load_dwordx4 v[252:255], v130, s[0:1]
	v_add_u32_e32 v130, 0x2000, v130
	global_load_dwordx4 v[252:255], v130, s[0:1]
	v_add_u32_e32 v130, 0x2000, v130
	s_waitcnt vmcnt(34)
	ds_write_b128 v118, v[70:73] offset:32768
	ds_write_b128 v119, v[74:77] offset:32768
	ds_write_b128 v120, v[78:81] offset:32768
	ds_write_b128 v121, v[82:85] offset:32768
	v_add_u32_e32 v118, 0x10000, v118
	v_add_u32_e32 v119, 0x10000, v119
	v_add_u32_e32 v120, 0x10000, v120
	v_add_u32_e32 v121, 0x10000, v121
	ds_write_b128 v118, v[86:89]
	ds_write_b128 v119, v[90:93]
	ds_write_b128 v120, v[94:97]
	ds_write_b128 v121, v[98:101]
	ds_write_b128 v118, v[102:105] offset:32768
	ds_write_b128 v119, v[106:109] offset:32768
	ds_write_b128 v120, v[110:113] offset:32768
	ds_write_b128 v121, v[114:117] offset:32768
	s_waitcnt lgkmcnt(0)
	s_barrier
	s_lshl_b32 s2, s50, 6
	v_or_b32_e32 v2, s2, v229
	v_ashrrev_i32_e32 v3, 31, v2
	v_bitop3_b32 v5, s2, v232, v229 bitop3:0xc8
	v_or_b32_e32 v4, 16, v2
	v_lshlrev_b64 v[174:175], 12, v[2:3]
	v_lshlrev_b64 v[6:7], 11, v[2:3]
	v_or_b32_e32 v8, 32, v2
	v_or_b32_e32 v2, 48, v2
	v_cmp_lt_u32_e32 vcc, 2, v5
	v_cmp_lt_u32_e64 s[2:3], 1, v5
	v_cmp_ne_u32_e64 s[4:5], 0, v5
	v_ashrrev_i32_e32 v5, 31, v4
	v_ashrrev_i32_e32 v9, 31, v8
	v_ashrrev_i32_e32 v3, 31, v2
	v_lshlrev_b64 v[188:189], 12, v[4:5]
	v_lshlrev_b64 v[196:197], 12, v[8:9]
	v_lshlrev_b64 v[4:5], 11, v[4:5]
	v_lshlrev_b64 v[204:205], 12, v[2:3]
	v_lshlrev_b64 v[8:9], 11, v[8:9]
	v_lshlrev_b64 v[2:3], 11, v[2:3]
	v_lshl_add_u64 v[176:177], v[174:175], 0, s[14:15]
	v_lshl_add_u64 v[178:179], v[174:175], 0, s[16:17]
	v_lshl_add_u64 v[180:181], v[174:175], 0, s[18:19]
	v_lshl_add_u64 v[182:183], v[174:175], 0, s[20:21]
	v_lshl_add_u64 v[184:185], v[174:175], 0, s[22:23]
	v_lshl_add_u64 v[186:187], v[174:175], 0, s[24:25]
	v_lshl_add_u64 v[190:191], v[174:175], 0, s[26:27]
	v_lshl_add_u64 v[192:193], v[174:175], 0, s[28:29]
	v_lshl_add_u64 v[194:195], v[174:175], 0, s[30:31]
	v_lshl_add_u64 v[198:199], v[174:175], 0, s[34:35]
	v_lshl_add_u64 v[200:201], v[174:175], 0, s[36:37]
	v_lshl_add_u64 v[202:203], v[174:175], 0, s[38:39]
	v_lshlrev_b64 v[206:207], 1, v[6:7]
	v_lshlrev_b64 v[208:209], 1, v[4:5]
	v_lshlrev_b64 v[210:211], 1, v[8:9]
	v_lshlrev_b64 v[212:213], 1, v[2:3]
	s_mov_b32 s51, 0
	v_mov_b32_e32 v66, v163
	v_mov_b32_e32 v67, v163
	v_mov_b32_e32 v68, v163
	v_mov_b32_e32 v69, v163
	v_mov_b32_e32 v62, v163
	v_mov_b32_e32 v63, v163
	v_mov_b32_e32 v64, v163
	v_mov_b32_e32 v65, v163
	v_mov_b32_e32 v2, v163
	v_mov_b32_e32 v3, v163
	v_mov_b32_e32 v4, v163
	v_mov_b32_e32 v5, v163
	v_mov_b32_e32 v6, v163
	v_mov_b32_e32 v7, v163
	v_mov_b32_e32 v8, v163
	v_mov_b32_e32 v9, v163
	s_branch .LBB0_301
